# v12 + oddmix conv: two serial pk_fma accumulation chains interleaved (60 s_nops per iteration removed), bit-identical
# baseline (speedup 1.0000x reference)
; #define LAS __attribute__((address_space(3)))
; __device__ __forceinline__ void oddmix_phase(const Args& a, int li, LAS unsigned char* lds) {
;     ...
;         for (int ob = 0; ob < 4; ++ob) { float xin[38];
; #pragma unroll
;             for (int i = 0; i < 38; ++i) xin[i] = bf1(*(const LAS bf16*)(lds + OM_GL + (ob * 8 + i) * 1024 + tid * 2));
; #pragma unroll
;             for (int t = 0; t < 8; ++t) { float acc = cb;
; #pragma unroll
;                 for (int k = 0; k < 31; ++k) acc += cw[k] * xin[t + k];
;                 *(LAS float*)(lds + OM_CV + (ob * 8 + t) * 2048 + tid * 4) = acc; } }
.LBB0_293:
	v_lshl_add_u32 v168, s1, 13, v147
	v_lshl_add_u32 v170, s0, 13, v147
	ds_read_u16 v16, v168
	ds_read_u16 v17, v170
	v_lshl_add_u32 v173, s0, 14, v204
	v_add_u32_e32 v178, 0xf800, v173
	s_add_i32 s0, s0, 2
	s_waitcnt lgkmcnt(1)
	v_lshlrev_b32_e32 v202, 16, v16
	s_waitcnt lgkmcnt(0)
	v_lshlrev_b32_e32 v203, 16, v17
	ds_read_u16 v16, v168 offset:1024
	ds_read_u16 v17, v170 offset:1024
	s_add_i32 s2, s2, -2
	s_waitcnt lgkmcnt(1)
	v_lshlrev_b32_e32 v200, 16, v16
	s_waitcnt lgkmcnt(0)
	v_lshlrev_b32_e32 v201, 16, v17
	ds_read_u16 v16, v168 offset:2048
	ds_read_u16 v17, v170 offset:2048
	s_waitcnt lgkmcnt(1)
	v_lshlrev_b32_e32 v198, 16, v16
	s_waitcnt lgkmcnt(0)
	v_lshlrev_b32_e32 v199, 16, v17
	ds_read_u16 v16, v168 offset:3072
	ds_read_u16 v17, v170 offset:3072
	s_waitcnt lgkmcnt(1)
	v_lshlrev_b32_e32 v196, 16, v16
	s_waitcnt lgkmcnt(0)
	v_lshlrev_b32_e32 v197, 16, v17
	ds_read_u16 v16, v168 offset:4096
	ds_read_u16 v17, v170 offset:4096
	s_waitcnt lgkmcnt(1)
	v_lshlrev_b32_e32 v192, 16, v16
	s_waitcnt lgkmcnt(0)
	v_lshlrev_b32_e32 v193, 16, v17
	ds_read_u16 v16, v168 offset:5120
	ds_read_u16 v17, v170 offset:5120
	s_waitcnt lgkmcnt(1)
	v_lshlrev_b32_e32 v58, 16, v16
	s_waitcnt lgkmcnt(0)
	v_lshlrev_b32_e32 v59, 16, v17
	ds_read_u16 v16, v168 offset:6144
	ds_read_u16 v17, v170 offset:6144
	s_waitcnt lgkmcnt(1)
	v_lshlrev_b32_e32 v36, 16, v16
	s_waitcnt lgkmcnt(0)
	v_lshlrev_b32_e32 v37, 16, v17
	ds_read_u16 v16, v168 offset:7168
	ds_read_u16 v17, v170 offset:7168
	ds_read_u16 v18, v168 offset:8192
	ds_read_u16 v19, v170 offset:8192
	ds_read_u16 v20, v168 offset:9216
	ds_read_u16 v21, v170 offset:9216
	ds_read_u16 v22, v168 offset:10240
	ds_read_u16 v23, v170 offset:10240
	ds_read_u16 v24, v168 offset:11264
	ds_read_u16 v25, v170 offset:11264
	ds_read_u16 v26, v168 offset:12288
	ds_read_u16 v27, v170 offset:12288
	ds_read_u16 v28, v168 offset:13312
	ds_read_u16 v29, v170 offset:13312
	ds_read_u16 v30, v168 offset:14336
	ds_read_u16 v31, v170 offset:14336
	ds_read_u16 v32, v168 offset:15360
	ds_read_u16 v33, v170 offset:15360
	ds_read_u16 v34, v168 offset:16384
	ds_read_u16 v35, v170 offset:16384
	ds_read_u16 v38, v168 offset:17408
	ds_read_u16 v39, v170 offset:17408
	ds_read_u16 v40, v168 offset:18432
	ds_read_u16 v41, v170 offset:18432
	ds_read_u16 v42, v168 offset:19456
	ds_read_u16 v43, v170 offset:19456
	ds_read_u16 v44, v168 offset:20480
	ds_read_u16 v45, v170 offset:20480
	ds_read_u16 v46, v168 offset:21504
	ds_read_u16 v47, v170 offset:21504
	ds_read_u16 v48, v168 offset:22528
	ds_read_u16 v49, v170 offset:22528
	ds_read_u16 v50, v168 offset:23552
	ds_read_u16 v51, v170 offset:23552
	ds_read_u16 v52, v168 offset:24576
	ds_read_u16 v53, v170 offset:24576
	ds_read_u16 v54, v168 offset:25600
	ds_read_u16 v55, v170 offset:25600
	ds_read_u16 v56, v168 offset:26624
	ds_read_u16 v57, v170 offset:26624
	ds_read_u16 v60, v168 offset:27648
	ds_read_u16 v61, v170 offset:27648
	ds_read_u16 v62, v168 offset:28672
	ds_read_u16 v63, v170 offset:28672
	ds_read_u16 v64, v168 offset:29696
	ds_read_u16 v65, v170 offset:29696
	ds_read_u16 v66, v168 offset:30720
	ds_read_u16 v67, v170 offset:30720
	ds_read_u16 v68, v168 offset:31744
	ds_read_u16 v69, v170 offset:31744
	ds_read_u16 v70, v168 offset:32768
	ds_read_u16 v71, v170 offset:32768
	ds_read_u16 v72, v168 offset:33792
	ds_read_u16 v73, v170 offset:33792
	ds_read_u16 v74, v168 offset:34816
	ds_read_u16 v75, v170 offset:34816
	ds_read_u16 v76, v168 offset:35840
	ds_read_u16 v77, v170 offset:35840
	ds_read_u16 v78, v168 offset:36864
	ds_read_u16 v79, v170 offset:36864
	ds_read_u16 v168, v168 offset:37888
	ds_read_u16 v170, v170 offset:37888
	s_waitcnt lgkmcnt(14)
	v_lshlrev_b32_e32 v17, 16, v17
	v_lshlrev_b32_e32 v16, 16, v16
	v_lshlrev_b32_e32 v19, 16, v19
	v_lshlrev_b32_e32 v18, 16, v18
	s_waitcnt lgkmcnt(0)
	v_lshlrev_b32_e32 v195, 16, v170
	v_pk_fma_f32 v[170:171], v[114:115], v[202:203], v[130:131]
	v_lshlrev_b32_e32 v21, 16, v21
	v_pk_fma_f32 v[170:171], v[116:117], v[200:201], v[170:171]
	v_lshlrev_b32_e32 v20, 16, v20
	v_pk_fma_f32 v[170:171], v[82:83], v[198:199], v[170:171]
	v_lshlrev_b32_e32 v23, 16, v23
	v_pk_fma_f32 v[170:171], v[118:119], v[196:197], v[170:171]
	v_lshlrev_b32_e32 v22, 16, v22
	v_pk_fma_f32 v[170:171], v[84:85], v[192:193], v[170:171]
	v_lshlrev_b32_e32 v25, 16, v25
	v_pk_fma_f32 v[170:171], v[86:87], v[58:59], v[170:171]
	v_lshlrev_b32_e32 v24, 16, v24
	v_pk_fma_f32 v[170:171], v[88:89], v[36:37], v[170:171]
	v_lshlrev_b32_e32 v27, 16, v27
	v_pk_fma_f32 v[170:171], v[120:121], v[16:17], v[170:171]
	v_lshlrev_b32_e32 v26, 16, v26
	v_pk_fma_f32 v[170:171], v[90:91], v[18:19], v[170:171]
	v_lshlrev_b32_e32 v29, 16, v29
	v_pk_fma_f32 v[170:171], v[92:93], v[20:21], v[170:171]
	v_lshlrev_b32_e32 v28, 16, v28
	v_pk_fma_f32 v[170:171], v[94:95], v[22:23], v[170:171]
	v_lshlrev_b32_e32 v31, 16, v31
	v_pk_fma_f32 v[170:171], v[122:123], v[24:25], v[170:171]
	v_lshlrev_b32_e32 v30, 16, v30
	v_pk_fma_f32 v[170:171], v[96:97], v[26:27], v[170:171]
	v_lshlrev_b32_e32 v33, 16, v33
	v_pk_fma_f32 v[170:171], v[98:99], v[28:29], v[170:171]
	v_lshlrev_b32_e32 v32, 16, v32
	v_pk_fma_f32 v[170:171], v[100:101], v[30:31], v[170:171]
	v_lshlrev_b32_e32 v35, 16, v35
	v_lshlrev_b32_e32 v34, 16, v34
	v_pk_fma_f32 v[170:171], v[124:125], v[32:33], v[170:171]
	v_lshlrev_b32_e32 v39, 16, v39
	v_lshlrev_b32_e32 v38, 16, v38
	v_pk_fma_f32 v[170:171], v[102:103], v[34:35], v[170:171]
	v_lshlrev_b32_e32 v41, 16, v41
	v_lshlrev_b32_e32 v40, 16, v40
	v_pk_fma_f32 v[170:171], v[104:105], v[38:39], v[170:171]
	v_lshlrev_b32_e32 v43, 16, v43
	v_lshlrev_b32_e32 v42, 16, v42
; #define LAS __attribute__((address_space(3)))
; __device__ __forceinline__ void oddmix_phase(const Args& a, int li, LAS unsigned char* lds) {
;     ...
;         for (int ob = 0; ob < 4; ++ob) { float xin[38];
; #pragma unroll
;             for (int i = 0; i < 38; ++i) xin[i] = bf1(*(const LAS bf16*)(lds + OM_GL + (ob * 8 + i) * 1024 + tid * 2));
; #pragma unroll
;             for (int t = 0; t < 8; ++t) { float acc = cb;
; #pragma unroll
;                 for (int k = 0; k < 31; ++k) acc += cw[k] * xin[t + k];
;                 *(LAS float*)(lds + OM_CV + (ob * 8 + t) * 2048 + tid * 4) = acc; } }
	v_pk_fma_f32 v[170:171], v[106:107], v[40:41], v[170:171]
	v_lshlrev_b32_e32 v45, 16, v45
	v_lshlrev_b32_e32 v44, 16, v44
	v_pk_fma_f32 v[170:171], v[126:127], v[42:43], v[170:171]
	v_lshlrev_b32_e32 v47, 16, v47
	v_lshlrev_b32_e32 v46, 16, v46
	v_pk_fma_f32 v[170:171], v[108:109], v[44:45], v[170:171]
	v_lshlrev_b32_e32 v49, 16, v49
	v_lshlrev_b32_e32 v48, 16, v48
	v_pk_fma_f32 v[170:171], v[110:111], v[46:47], v[170:171]
	v_lshlrev_b32_e32 v51, 16, v51
	v_lshlrev_b32_e32 v50, 16, v50
	v_pk_fma_f32 v[170:171], v[112:113], v[48:49], v[170:171]
	v_lshlrev_b32_e32 v53, 16, v53
	v_lshlrev_b32_e32 v52, 16, v52
	v_pk_fma_f32 v[170:171], v[128:129], v[50:51], v[170:171]
	v_lshlrev_b32_e32 v55, 16, v55
	v_lshlrev_b32_e32 v54, 16, v54
	v_pk_fma_f32 v[170:171], v[132:133], v[52:53], v[170:171]
	v_lshlrev_b32_e32 v57, 16, v57
	v_lshlrev_b32_e32 v56, 16, v56
	v_pk_fma_f32 v[170:171], v[134:135], v[54:55], v[170:171]
	v_lshlrev_b32_e32 v61, 16, v61
	v_lshlrev_b32_e32 v60, 16, v60
	v_pk_fma_f32 v[170:171], v[136:137], v[56:57], v[170:171]
	v_lshlrev_b32_e32 v63, 16, v63
	v_lshlrev_b32_e32 v62, 16, v62
	v_pk_fma_f32 v[170:171], v[142:143], v[60:61], v[170:171]
	v_lshlrev_b32_e32 v65, 16, v65
	v_lshlrev_b32_e32 v64, 16, v64
	v_pk_fma_f32 v[170:171], v[138:139], v[62:63], v[170:171]
	v_lshlrev_b32_e32 v67, 16, v67
	v_lshlrev_b32_e32 v66, 16, v66
	v_pk_fma_f32 v[170:171], v[140:141], v[64:65], v[170:171]
	v_lshlrev_b32_e32 v194, 16, v168
	v_lshl_add_u32 v168, s1, 14, v204
	v_pk_fma_f32 v[170:171], v[144:145], v[66:67], v[170:171]
	ds_write_b32 v168, v170 offset:63488
	ds_write_b32 v173, v171 offset:63488
	v_pk_fma_f32 v[170:171], v[114:115], v[200:201], v[130:131]
	v_lshlrev_b32_e32 v69, 16, v69
	v_pk_fma_f32 v[170:171], v[116:117], v[198:199], v[170:171]
	v_lshlrev_b32_e32 v68, 16, v68
	v_pk_fma_f32 v[170:171], v[82:83], v[196:197], v[170:171]
	v_add_u32_e32 v172, 0xf800, v168
	v_pk_fma_f32 v[170:171], v[118:119], v[192:193], v[170:171]
	v_lshlrev_b32_e32 v71, 16, v71
	v_pk_fma_f32 v[170:171], v[84:85], v[58:59], v[170:171]
	v_lshlrev_b32_e32 v70, 16, v70
	v_pk_fma_f32 v[170:171], v[86:87], v[36:37], v[170:171]
	v_lshlrev_b32_e32 v73, 16, v73
	v_pk_fma_f32 v[170:171], v[88:89], v[16:17], v[170:171]
	v_lshlrev_b32_e32 v72, 16, v72
	v_pk_fma_f32 v[170:171], v[120:121], v[18:19], v[170:171]
	v_lshlrev_b32_e32 v75, 16, v75
	v_pk_fma_f32 v[170:171], v[90:91], v[20:21], v[170:171]
	v_lshlrev_b32_e32 v74, 16, v74
	v_pk_fma_f32 v[170:171], v[92:93], v[22:23], v[170:171]
	v_lshlrev_b32_e32 v77, 16, v77
	v_pk_fma_f32 v[170:171], v[94:95], v[24:25], v[170:171]
	v_lshlrev_b32_e32 v76, 16, v76
	v_pk_fma_f32 v[170:171], v[122:123], v[26:27], v[170:171]
	v_lshlrev_b32_e32 v79, 16, v79
	v_pk_fma_f32 v[170:171], v[96:97], v[28:29], v[170:171]
	v_lshlrev_b32_e32 v78, 16, v78
	v_pk_fma_f32 v[170:171], v[98:99], v[30:31], v[170:171]
	s_add_i32 s1, s1, 2
	v_pk_fma_f32 v[170:171], v[100:101], v[32:33], v[170:171]
	s_cmp_lg_u32 s2, 0
	v_pk_fma_f32 v[170:171], v[124:125], v[34:35], v[170:171]
	s_nop 0
	v_pk_fma_f32 v[170:171], v[102:103], v[38:39], v[170:171]
	s_nop 0
	v_pk_fma_f32 v[170:171], v[104:105], v[40:41], v[170:171]
	s_nop 0
	v_pk_fma_f32 v[170:171], v[106:107], v[42:43], v[170:171]
	s_nop 0
	v_pk_fma_f32 v[170:171], v[126:127], v[44:45], v[170:171]
	s_nop 0
	v_pk_fma_f32 v[170:171], v[108:109], v[46:47], v[170:171]
	s_nop 0
	v_pk_fma_f32 v[170:171], v[110:111], v[48:49], v[170:171]
	s_nop 0
	v_pk_fma_f32 v[170:171], v[112:113], v[50:51], v[170:171]
	s_nop 0
	v_pk_fma_f32 v[170:171], v[128:129], v[52:53], v[170:171]
	s_nop 0
	v_pk_fma_f32 v[170:171], v[132:133], v[54:55], v[170:171]
	s_nop 0
	v_pk_fma_f32 v[170:171], v[134:135], v[56:57], v[170:171]
	s_nop 0
	v_pk_fma_f32 v[170:171], v[136:137], v[60:61], v[170:171]
	s_nop 0
	v_pk_fma_f32 v[170:171], v[142:143], v[62:63], v[170:171]
	s_nop 0
	v_pk_fma_f32 v[170:171], v[138:139], v[64:65], v[170:171]
	s_nop 0
	v_pk_fma_f32 v[170:171], v[140:141], v[66:67], v[170:171]
	s_nop 0
	v_pk_fma_f32 v[170:171], v[144:145], v[68:69], v[170:171]
	ds_write_b32 v172, v170 offset:2048
	ds_write_b32 v178, v171 offset:2048
	v_pk_fma_f32 v[170:171], v[114:115], v[198:199], v[130:131]
	v_pk_fma_f32 v[214:215], v[114:115], v[196:197], v[130:131]
	v_pk_fma_f32 v[170:171], v[116:117], v[196:197], v[170:171]
	v_pk_fma_f32 v[214:215], v[116:117], v[192:193], v[214:215]
	v_pk_fma_f32 v[170:171], v[82:83], v[192:193], v[170:171]
	v_pk_fma_f32 v[214:215], v[82:83], v[58:59], v[214:215]
	v_pk_fma_f32 v[170:171], v[118:119], v[58:59], v[170:171]
	v_pk_fma_f32 v[214:215], v[118:119], v[36:37], v[214:215]
	v_pk_fma_f32 v[170:171], v[84:85], v[36:37], v[170:171]
	v_pk_fma_f32 v[214:215], v[84:85], v[16:17], v[214:215]
	v_pk_fma_f32 v[170:171], v[86:87], v[16:17], v[170:171]
	v_pk_fma_f32 v[214:215], v[86:87], v[18:19], v[214:215]
	v_pk_fma_f32 v[170:171], v[88:89], v[18:19], v[170:171]
	v_pk_fma_f32 v[214:215], v[88:89], v[20:21], v[214:215]
	v_pk_fma_f32 v[170:171], v[120:121], v[20:21], v[170:171]
	v_pk_fma_f32 v[214:215], v[120:121], v[22:23], v[214:215]
	v_pk_fma_f32 v[170:171], v[90:91], v[22:23], v[170:171]
	v_pk_fma_f32 v[214:215], v[90:91], v[24:25], v[214:215]
	v_pk_fma_f32 v[170:171], v[92:93], v[24:25], v[170:171]
	v_pk_fma_f32 v[214:215], v[92:93], v[26:27], v[214:215]
	v_pk_fma_f32 v[170:171], v[94:95], v[26:27], v[170:171]
	v_pk_fma_f32 v[214:215], v[94:95], v[28:29], v[214:215]
	v_pk_fma_f32 v[170:171], v[122:123], v[28:29], v[170:171]
	v_pk_fma_f32 v[214:215], v[122:123], v[30:31], v[214:215]
	v_pk_fma_f32 v[170:171], v[96:97], v[30:31], v[170:171]
	v_pk_fma_f32 v[214:215], v[96:97], v[32:33], v[214:215]
; #define LAS __attribute__((address_space(3)))
; __device__ __forceinline__ void oddmix_phase(const Args& a, int li, LAS unsigned char* lds) {
;     ...
;         for (int ob = 0; ob < 4; ++ob) { float xin[38];
; #pragma unroll
;             for (int i = 0; i < 38; ++i) xin[i] = bf1(*(const LAS bf16*)(lds + OM_GL + (ob * 8 + i) * 1024 + tid * 2));
; #pragma unroll
;             for (int t = 0; t < 8; ++t) { float acc = cb;
; #pragma unroll
;                 for (int k = 0; k < 31; ++k) acc += cw[k] * xin[t + k];
;                 *(LAS float*)(lds + OM_CV + (ob * 8 + t) * 2048 + tid * 4) = acc; } }
	v_pk_fma_f32 v[170:171], v[98:99], v[32:33], v[170:171]
	v_pk_fma_f32 v[214:215], v[98:99], v[34:35], v[214:215]
	v_pk_fma_f32 v[170:171], v[100:101], v[34:35], v[170:171]
	v_pk_fma_f32 v[214:215], v[100:101], v[38:39], v[214:215]
	v_pk_fma_f32 v[170:171], v[124:125], v[38:39], v[170:171]
	v_pk_fma_f32 v[214:215], v[124:125], v[40:41], v[214:215]
	v_pk_fma_f32 v[170:171], v[102:103], v[40:41], v[170:171]
	v_pk_fma_f32 v[214:215], v[102:103], v[42:43], v[214:215]
	v_pk_fma_f32 v[170:171], v[104:105], v[42:43], v[170:171]
	v_pk_fma_f32 v[214:215], v[104:105], v[44:45], v[214:215]
	v_pk_fma_f32 v[170:171], v[106:107], v[44:45], v[170:171]
	v_pk_fma_f32 v[214:215], v[106:107], v[46:47], v[214:215]
	v_pk_fma_f32 v[170:171], v[126:127], v[46:47], v[170:171]
	v_pk_fma_f32 v[214:215], v[126:127], v[48:49], v[214:215]
	v_pk_fma_f32 v[170:171], v[108:109], v[48:49], v[170:171]
	v_pk_fma_f32 v[214:215], v[108:109], v[50:51], v[214:215]
	v_pk_fma_f32 v[170:171], v[110:111], v[50:51], v[170:171]
	v_pk_fma_f32 v[214:215], v[110:111], v[52:53], v[214:215]
	v_pk_fma_f32 v[170:171], v[112:113], v[52:53], v[170:171]
	v_pk_fma_f32 v[214:215], v[112:113], v[54:55], v[214:215]
	v_pk_fma_f32 v[170:171], v[128:129], v[54:55], v[170:171]
	v_pk_fma_f32 v[214:215], v[128:129], v[56:57], v[214:215]
	v_pk_fma_f32 v[170:171], v[132:133], v[56:57], v[170:171]
	v_pk_fma_f32 v[214:215], v[132:133], v[60:61], v[214:215]
	v_pk_fma_f32 v[170:171], v[134:135], v[60:61], v[170:171]
	v_pk_fma_f32 v[214:215], v[134:135], v[62:63], v[214:215]
	v_pk_fma_f32 v[170:171], v[136:137], v[62:63], v[170:171]
	v_pk_fma_f32 v[214:215], v[136:137], v[64:65], v[214:215]
	v_pk_fma_f32 v[170:171], v[142:143], v[64:65], v[170:171]
	v_pk_fma_f32 v[214:215], v[142:143], v[66:67], v[214:215]
	v_pk_fma_f32 v[170:171], v[138:139], v[66:67], v[170:171]
	v_pk_fma_f32 v[214:215], v[138:139], v[68:69], v[214:215]
	v_pk_fma_f32 v[170:171], v[140:141], v[68:69], v[170:171]
	v_pk_fma_f32 v[214:215], v[140:141], v[70:71], v[214:215]
	v_pk_fma_f32 v[170:171], v[144:145], v[70:71], v[170:171]
	v_pk_fma_f32 v[214:215], v[144:145], v[72:73], v[214:215]
	ds_write_b32 v172, v170 offset:4096
	ds_write_b32 v178, v171 offset:4096
	ds_write_b32 v172, v214 offset:6144
	ds_write_b32 v178, v215 offset:6144
	v_pk_fma_f32 v[170:171], v[114:115], v[192:193], v[130:131]
	s_nop 0
	v_pk_fma_f32 v[170:171], v[116:117], v[58:59], v[170:171]
	v_pk_fma_f32 v[58:59], v[114:115], v[58:59], v[130:131]
	v_pk_fma_f32 v[170:171], v[82:83], v[36:37], v[170:171]
	v_pk_fma_f32 v[58:59], v[116:117], v[36:37], v[58:59]
	v_pk_fma_f32 v[36:37], v[114:115], v[36:37], v[130:131]
	v_pk_fma_f32 v[170:171], v[118:119], v[16:17], v[170:171]
	v_pk_fma_f32 v[58:59], v[82:83], v[16:17], v[58:59]
	v_pk_fma_f32 v[36:37], v[116:117], v[16:17], v[36:37]
	v_pk_fma_f32 v[16:17], v[114:115], v[16:17], v[130:131]
	v_pk_fma_f32 v[36:37], v[82:83], v[18:19], v[36:37]
	v_pk_fma_f32 v[16:17], v[116:117], v[18:19], v[16:17]
	v_pk_fma_f32 v[58:59], v[118:119], v[18:19], v[58:59]
	v_pk_fma_f32 v[16:17], v[82:83], v[20:21], v[16:17]
	v_pk_fma_f32 v[36:37], v[118:119], v[20:21], v[36:37]
	v_pk_fma_f32 v[16:17], v[118:119], v[22:23], v[16:17]
	v_pk_fma_f32 v[170:171], v[84:85], v[18:19], v[170:171]
	v_pk_fma_f32 v[58:59], v[84:85], v[20:21], v[58:59]
	v_pk_fma_f32 v[36:37], v[84:85], v[22:23], v[36:37]
	v_pk_fma_f32 v[16:17], v[84:85], v[24:25], v[16:17]
	v_pk_fma_f32 v[170:171], v[86:87], v[20:21], v[170:171]
	v_pk_fma_f32 v[58:59], v[86:87], v[22:23], v[58:59]
	v_pk_fma_f32 v[36:37], v[86:87], v[24:25], v[36:37]
	v_pk_fma_f32 v[16:17], v[86:87], v[26:27], v[16:17]
	v_pk_fma_f32 v[170:171], v[88:89], v[22:23], v[170:171]
	v_pk_fma_f32 v[58:59], v[88:89], v[24:25], v[58:59]
	v_pk_fma_f32 v[36:37], v[88:89], v[26:27], v[36:37]
	v_pk_fma_f32 v[16:17], v[88:89], v[28:29], v[16:17]
	v_pk_fma_f32 v[170:171], v[120:121], v[24:25], v[170:171]
	v_pk_fma_f32 v[58:59], v[120:121], v[26:27], v[58:59]
	v_pk_fma_f32 v[36:37], v[120:121], v[28:29], v[36:37]
	v_pk_fma_f32 v[16:17], v[120:121], v[30:31], v[16:17]
	v_pk_fma_f32 v[170:171], v[90:91], v[26:27], v[170:171]
	v_pk_fma_f32 v[58:59], v[90:91], v[28:29], v[58:59]
	v_pk_fma_f32 v[36:37], v[90:91], v[30:31], v[36:37]
	v_pk_fma_f32 v[16:17], v[90:91], v[32:33], v[16:17]
	v_pk_fma_f32 v[170:171], v[92:93], v[28:29], v[170:171]
	v_pk_fma_f32 v[58:59], v[92:93], v[30:31], v[58:59]
	v_pk_fma_f32 v[36:37], v[92:93], v[32:33], v[36:37]
	v_pk_fma_f32 v[16:17], v[92:93], v[34:35], v[16:17]
	v_pk_fma_f32 v[170:171], v[94:95], v[30:31], v[170:171]
	v_pk_fma_f32 v[58:59], v[94:95], v[32:33], v[58:59]
	v_pk_fma_f32 v[36:37], v[94:95], v[34:35], v[36:37]
	v_pk_fma_f32 v[16:17], v[94:95], v[38:39], v[16:17]
	v_pk_fma_f32 v[170:171], v[122:123], v[32:33], v[170:171]
	v_pk_fma_f32 v[58:59], v[122:123], v[34:35], v[58:59]
; #define LAS __attribute__((address_space(3)))
; __device__ __forceinline__ void oddmix_phase(const Args& a, int li, LAS unsigned char* lds) {
;     ...
;         for (int ob = 0; ob < 4; ++ob) { float xin[38];
; #pragma unroll
;             for (int i = 0; i < 38; ++i) xin[i] = bf1(*(const LAS bf16*)(lds + OM_GL + (ob * 8 + i) * 1024 + tid * 2));
; #pragma unroll
;             for (int t = 0; t < 8; ++t) { float acc = cb;
; #pragma unroll
;                 for (int k = 0; k < 31; ++k) acc += cw[k] * xin[t + k];
;                 *(LAS float*)(lds + OM_CV + (ob * 8 + t) * 2048 + tid * 4) = acc; } }
	v_pk_fma_f32 v[36:37], v[122:123], v[38:39], v[36:37]
	v_pk_fma_f32 v[16:17], v[122:123], v[40:41], v[16:17]
	v_pk_fma_f32 v[170:171], v[96:97], v[34:35], v[170:171]
	v_pk_fma_f32 v[58:59], v[96:97], v[38:39], v[58:59]
	v_pk_fma_f32 v[36:37], v[96:97], v[40:41], v[36:37]
	v_pk_fma_f32 v[16:17], v[96:97], v[42:43], v[16:17]
	v_pk_fma_f32 v[170:171], v[98:99], v[38:39], v[170:171]
	v_pk_fma_f32 v[58:59], v[98:99], v[40:41], v[58:59]
	v_pk_fma_f32 v[36:37], v[98:99], v[42:43], v[36:37]
	v_pk_fma_f32 v[16:17], v[98:99], v[44:45], v[16:17]
	v_pk_fma_f32 v[170:171], v[100:101], v[40:41], v[170:171]
	v_pk_fma_f32 v[58:59], v[100:101], v[42:43], v[58:59]
	v_pk_fma_f32 v[36:37], v[100:101], v[44:45], v[36:37]
	v_pk_fma_f32 v[16:17], v[100:101], v[46:47], v[16:17]
	v_pk_fma_f32 v[170:171], v[124:125], v[42:43], v[170:171]
	v_pk_fma_f32 v[58:59], v[124:125], v[44:45], v[58:59]
	v_pk_fma_f32 v[36:37], v[124:125], v[46:47], v[36:37]
	v_pk_fma_f32 v[16:17], v[124:125], v[48:49], v[16:17]
	v_pk_fma_f32 v[170:171], v[102:103], v[44:45], v[170:171]
	v_pk_fma_f32 v[58:59], v[102:103], v[46:47], v[58:59]
	v_pk_fma_f32 v[36:37], v[102:103], v[48:49], v[36:37]
	v_pk_fma_f32 v[16:17], v[102:103], v[50:51], v[16:17]
	v_pk_fma_f32 v[170:171], v[104:105], v[46:47], v[170:171]
	v_pk_fma_f32 v[58:59], v[104:105], v[48:49], v[58:59]
	v_pk_fma_f32 v[36:37], v[104:105], v[50:51], v[36:37]
	v_pk_fma_f32 v[16:17], v[104:105], v[52:53], v[16:17]
	v_pk_fma_f32 v[170:171], v[106:107], v[48:49], v[170:171]
	v_pk_fma_f32 v[58:59], v[106:107], v[50:51], v[58:59]
	v_pk_fma_f32 v[36:37], v[106:107], v[52:53], v[36:37]
	v_pk_fma_f32 v[16:17], v[106:107], v[54:55], v[16:17]
	v_pk_fma_f32 v[170:171], v[126:127], v[50:51], v[170:171]
	v_pk_fma_f32 v[58:59], v[126:127], v[52:53], v[58:59]
	v_pk_fma_f32 v[36:37], v[126:127], v[54:55], v[36:37]
	v_pk_fma_f32 v[16:17], v[126:127], v[56:57], v[16:17]
	v_pk_fma_f32 v[170:171], v[108:109], v[52:53], v[170:171]
	v_pk_fma_f32 v[58:59], v[108:109], v[54:55], v[58:59]
	v_pk_fma_f32 v[36:37], v[108:109], v[56:57], v[36:37]
	v_pk_fma_f32 v[16:17], v[108:109], v[60:61], v[16:17]
	v_pk_fma_f32 v[170:171], v[110:111], v[54:55], v[170:171]
	v_pk_fma_f32 v[58:59], v[110:111], v[56:57], v[58:59]
	v_pk_fma_f32 v[36:37], v[110:111], v[60:61], v[36:37]
	v_pk_fma_f32 v[16:17], v[110:111], v[62:63], v[16:17]
	v_pk_fma_f32 v[170:171], v[112:113], v[56:57], v[170:171]
	v_pk_fma_f32 v[58:59], v[112:113], v[60:61], v[58:59]
	v_pk_fma_f32 v[36:37], v[112:113], v[62:63], v[36:37]
	v_pk_fma_f32 v[16:17], v[112:113], v[64:65], v[16:17]
	v_pk_fma_f32 v[170:171], v[128:129], v[60:61], v[170:171]
	v_pk_fma_f32 v[58:59], v[128:129], v[62:63], v[58:59]
	v_pk_fma_f32 v[36:37], v[128:129], v[64:65], v[36:37]
	v_pk_fma_f32 v[16:17], v[128:129], v[66:67], v[16:17]
	v_pk_fma_f32 v[170:171], v[132:133], v[62:63], v[170:171]
	v_pk_fma_f32 v[58:59], v[132:133], v[64:65], v[58:59]
	v_pk_fma_f32 v[36:37], v[132:133], v[66:67], v[36:37]
	v_pk_fma_f32 v[16:17], v[132:133], v[68:69], v[16:17]
	v_pk_fma_f32 v[170:171], v[134:135], v[64:65], v[170:171]
	v_pk_fma_f32 v[58:59], v[134:135], v[66:67], v[58:59]
	v_pk_fma_f32 v[36:37], v[134:135], v[68:69], v[36:37]
	v_pk_fma_f32 v[16:17], v[134:135], v[70:71], v[16:17]
	v_pk_fma_f32 v[170:171], v[136:137], v[66:67], v[170:171]
	v_pk_fma_f32 v[58:59], v[136:137], v[68:69], v[58:59]
	v_pk_fma_f32 v[36:37], v[136:137], v[70:71], v[36:37]
	v_pk_fma_f32 v[16:17], v[136:137], v[72:73], v[16:17]
	v_pk_fma_f32 v[170:171], v[142:143], v[68:69], v[170:171]
	v_pk_fma_f32 v[58:59], v[142:143], v[70:71], v[58:59]
	v_pk_fma_f32 v[36:37], v[142:143], v[72:73], v[36:37]
	v_pk_fma_f32 v[16:17], v[142:143], v[74:75], v[16:17]
	v_pk_fma_f32 v[170:171], v[138:139], v[70:71], v[170:171]
	v_pk_fma_f32 v[58:59], v[138:139], v[72:73], v[58:59]
	v_pk_fma_f32 v[36:37], v[138:139], v[74:75], v[36:37]
	v_pk_fma_f32 v[16:17], v[138:139], v[76:77], v[16:17]
	v_pk_fma_f32 v[170:171], v[140:141], v[72:73], v[170:171]
	v_pk_fma_f32 v[58:59], v[140:141], v[74:75], v[58:59]
	v_pk_fma_f32 v[36:37], v[140:141], v[76:77], v[36:37]
	v_pk_fma_f32 v[16:17], v[140:141], v[78:79], v[16:17]
	v_pk_fma_f32 v[170:171], v[144:145], v[74:75], v[170:171]
	v_pk_fma_f32 v[58:59], v[144:145], v[76:77], v[58:59]
	v_pk_fma_f32 v[36:37], v[144:145], v[78:79], v[36:37]
	v_pk_fma_f32 v[16:17], v[144:145], v[194:195], v[16:17]
	ds_write_b32 v172, v170 offset:8192
	ds_write_b32 v178, v171 offset:8192
	ds_write_b32 v172, v58 offset:10240
	ds_write_b32 v178, v59 offset:10240
	ds_write_b32 v172, v36 offset:12288
	ds_write_b32 v178, v37 offset:12288
	ds_write_b32 v172, v16 offset:14336
	ds_write_b32 v178, v17 offset:14336
	s_cbranch_scc1 .LBB0_293
	s_lshl_b64 s[26:27], s[60:61], 16
	v_lshl_add_u64 v[16:17], v[190:191], 0, s[26:27]
	s_mov_b32 s2, 0
	s_waitcnt lgkmcnt(0)
	s_barrier
